# speedup vs baseline: 1.0015x; 1.0015x over previous
; #define SWRITE(b, i) do { *(bf16x8*)(V_lds + (b) * SHM_VT + vst) = sr_[i].v0; \
;     *(bf16x8*)(K_lds + (b) * SHM_KT + kst0) = sr_[i].k0; *(bf16x8*)(K_lds + (b) * SHM_KT + kst1) = sr_[i].k1; } while (0)
; #define SWAIT() asm volatile("s_waitcnt vmcnt(3)" ::: "memory")
; #define RESC(a) do { if (__any((a) < 1.f)) { if (hi == 0) al_l[r32] = (a); asm volatile("s_waitcnt lgkmcnt(0)" ::: "memory"); \
;     _Pragma("unroll") for (int r = 0; r < 16; ++r) { const float a_ = al_l[crow(r, hi)]; o[0][r] *= a_; o[1][r] *= a_; o2[r] *= a_; } } } while (0)
; __device__ __forceinline__ void partialSM(f32x16& p0, f32x16& p1, float& m_reg, float& mn, float& alpha) {
;   constexpr float C = ATT_SCALE * 1.4426950408889634f;
;   float pmax = p0[0];
;   #pragma unroll
;   for (int r = 1; r < 16; ++r) pmax = fmaxf(pmax, p0[r]);
;   #pragma unroll
;   for (int r = 0; r < 16; ++r) pmax = fmaxf(pmax, p1[r]);
;   { auto rr = __builtin_amdgcn_permlane32_swap(__float_as_uint(pmax), __float_as_uint(pmax), false, false);
;     pmax = fmaxf(__uint_as_float(rr[0]), __uint_as_float(rr[1])); }
;   if (__builtin_expect(__all(pmax - m_reg <= THR / ATT_SCALE), 1)) { mn = m_reg; alpha = 1.f; }
;   else { mn = fmaxf(m_reg, pmax); alpha = __builtin_amdgcn_exp2f((m_reg - mn) * C); m_reg = mn; }
;   float mnC = -mn * C;
;   #pragma unroll
;   for (int r = 0; r < 16; ++r) p0[r] = fmaf(p0[r], C, mnC);
;   #pragma unroll
;   for (int r = 0; r < 16; ++r) p1[r] = fmaf(p1[r], C, mnC);
;   #pragma unroll
;   for (int r = 0; r < 16; ++r) p0[r] = __builtin_amdgcn_exp2f(p0[r]);
; __device__ __forceinline__ void attn_phase(const bf16* __restrict__ qbase, const bf16* __restrict__ Kbase, const bf16* __restrict__ Vbase, bf16* __restrict__ mixbase) {
;     ...
;       PVD(vb0 + SHM_VT); partialSM(pA0, pA1, m_reg, mnA, alA);
;       __syncthreads(); SWAIT(); if (j + 2 < NT) SWRITE(1, SO);
;       RESC(alA); __syncthreads();
.LBB0_539:
	v_cndmask_b32_e64 v181, v132, v148, s[0:1]
	v_mul_f32_e32 v132, 0xbe16c740, v181
	v_mov_b32_e32 v133, v132
	v_fmamk_f32 v48, v48, 0x3e16c740, v132
	v_fmamk_f32 v49, v49, 0x3e16c740, v132
	v_fmamk_f32 v50, v50, 0x3e16c740, v132
	v_fmamk_f32 v51, v51, 0x3e16c740, v132
	v_fmamk_f32 v52, v52, 0x3e16c740, v132
	v_fmamk_f32 v53, v53, 0x3e16c740, v132
	v_fmamk_f32 v54, v54, 0x3e16c740, v132
	v_fmamk_f32 v55, v55, 0x3e16c740, v132
	v_fmamk_f32 v56, v56, 0x3e16c740, v132
	v_fmamk_f32 v57, v57, 0x3e16c740, v132
	v_fmamk_f32 v58, v58, 0x3e16c740, v132
	v_fmamk_f32 v59, v59, 0x3e16c740, v132
	v_fmamk_f32 v60, v60, 0x3e16c740, v132
	v_fmamk_f32 v61, v61, 0x3e16c740, v132
	v_fmamk_f32 v62, v62, 0x3e16c740, v132
	v_fmac_f32_e32 v133, 0x3e16c740, v63
	v_exp_f32_e32 v226, v48
	v_exp_f32_e32 v230, v49
	v_exp_f32_e32 v227, v50
	v_exp_f32_e32 v231, v51
	v_exp_f32_e32 v228, v52
	v_exp_f32_e32 v232, v53
	v_exp_f32_e32 v225, v54
	v_exp_f32_e32 v229, v55
	v_exp_f32_e32 v206, v56
	v_exp_f32_e32 v223, v57
	v_exp_f32_e32 v207, v58
	v_exp_f32_e32 v224, v59
	v_exp_f32_e32 v205, v60
	v_exp_f32_e32 v222, v61
	v_exp_f32_e32 v204, v62
	v_exp_f32_e32 v221, v133
	s_add_i32 s41, s41, 2
	s_add_u32 s42, s42, 0x6000
	v_pk_fma_f32 v[152:153], v[64:65], s[2:3], v[132:133] op_sel_hi:[1,0,0]
	v_pk_fma_f32 v[150:151], v[66:67], s[2:3], v[132:133] op_sel_hi:[1,0,0]
	v_pk_fma_f32 v[148:149], v[68:69], s[2:3], v[132:133] op_sel_hi:[1,0,0]
	v_pk_fma_f32 v[146:147], v[70:71], s[2:3], v[132:133] op_sel_hi:[1,0,0]
	v_pk_fma_f32 v[144:145], v[72:73], s[2:3], v[132:133] op_sel_hi:[1,0,0]
	v_pk_fma_f32 v[158:159], v[74:75], s[2:3], v[132:133] op_sel_hi:[1,0,0]
	v_pk_fma_f32 v[156:157], v[76:77], s[2:3], v[132:133] op_sel_hi:[1,0,0]
	v_pk_fma_f32 v[154:155], v[78:79], s[2:3], v[132:133] op_sel_hi:[1,0,0]
	v_lshl_add_u64 v[198:199], v[198:199], 0, s[14:15]
	s_addc_u32 s43, s43, 0
	s_and_b64 vcc, exec, s[46:47]
	s_waitcnt lgkmcnt(0)
	s_barrier
	s_cbranch_vccnz .LBB0_509
	s_branch .LBB0_513
